# GEMM1: accumulator zeroing pass dropped, first K-tile pair of each unit peeled with C=0 on each accumulator's first MFMA
# speedup vs baseline: 1.0120x; 1.0070x over previous
; #define PG8_LDA(dst, b, h) do { _Pragma("unroll") for (int m = 0; m < 4; ++m) _Pragma("unroll") for (int k = 0; k < 2; ++k) dst[m][k] = *(const LAS bf16x8*)(lds + PG8_SA(b, h) + aoff + m * 2048 + k * 1024); } while (0)
; template <bool REMAP>
; DI void gemm_phase(LAS unsigned char* lds, const u16* A, int lda, const u16* Bt, int K, u16* O, int ldc, int nunits) {
;     ...
;     f32x4 acc[2][2][4][2];
; #pragma unroll
;     for (int a = 0; a < 2; ++a)
; #pragma unroll
;         for (int b = 0; b < 2; ++b)
; #pragma unroll
;             for (int m = 0; m < 4; ++m)
; #pragma unroll
;                 for (int n = 0; n < 2; ++n) acc[a][b][m][n] = (f32x4){0.f, 0.f, 0.f, 0.f};
;     bf16x8 At[4][2], B0[2][2], B1[2][2];
;     const char* cA = (const char*)A + (size_t)cur.pm * tstepA; const char* cB = (const char*)Bt + (size_t)cur.pn * tstepB;
;     PG8_STAGE(PG8_SB(0, 0), cB, voffB); PG8_STAGE(PG8_SA(0, 0), cA + akb(0), voffA); PG8_STAGE(PG8_SB(0, 1), cB + hstepB, voffB); PG8_STAGE(PG8_SA(0, 1), cA + akb(0) + hstepA, voffA);
;     if (wr == 1) PG8_BAR;
;     PG8_WAIT_V(4); PG8_BAR;
;     PG8_STAGE(PG8_SB(1, 0), cB + kstep, voffB); PG8_STAGE(PG8_SA(1, 0), cA + akb(1), voffA); PG8_STAGE(PG8_SB(1, 1), cB + hstepB + kstep, voffB);
;     PG8_WAIT_V(6); PG8_BAR;
;     for (;;) {
;         const bool has_next = next_unit(ui + 1, nunits, nxt);
;         const char* nA = has_next ? (const char*)A + (size_t)nxt.pm * tstepA : cA; const char* nB = has_next ? (const char*)Bt + (size_t)nxt.pn * tstepB : cB;
;         for (int t = 0; t < nt; t += 2) {
;             const bool last = (t == nt - 2);
;             const char* a1 = cA + akb(t + 1);
;             const char* a2 = last ? nA + akb(0) : cA + akb(t + 2); const char* b2 = last ? nB : cB + (size_t)(t + 2) * kstep;
;             const char* a3 = last ? nA + akb(1) : cA + akb(t + 3); const char* b3 = b2 + kstep;
;             PG8_LDB(B0, 0, 0); PG8_SCHED; PG8_LDA(At, 0, 0); PG8_STAGE(PG8_SA(1, 1), a1 + hstepA, voffA);
;             PG8_WAIT_L(8); PG8_BAR; PG8_WAIT_L(0); PG8_MMA(0, 0, At, B0); PG8_BAR; PG8_SCHED;
;             PG8_LDB(B1, 0, 1); PG8_STAGE(PG8_SB(0, 0), b2, voffB);
;             PG8_BAR; PG8_WAIT_L(0); PG8_MMA(0, 1, At, B1); PG8_BAR;
;             PG8_LDA(At, 0, 1); PG8_STAGE(PG8_SA(0, 0), a2, voffA);
;             PG8_BAR; PG8_WAIT_L(0); PG8_MMA(1, 0, At, B0); PG8_BAR; PG8_SCHED;
.LBB0_136:
	s_ashr_i32 s5, s4, 31
	s_lshl_b64 s[12:13], s[4:5], 19
	s_add_u32 s12, s3, s12
	s_addc_u32 s13, s24, s13
	s_and_b64 s[14:15], s[22:23], exec
	s_cselect_b32 s5, s13, s11
	s_cselect_b32 s46, s12, s10
	s_ashr_i32 s7, s6, 31
	s_lshl_b64 s[14:15], s[6:7], 19
	s_add_u32 s14, s16, s14
	s_addc_u32 s15, s25, s15
	s_and_b64 s[22:23], s[22:23], exec
	s_cselect_b32 s7, s15, s21
	s_cselect_b32 s47, s14, s20
	s_add_u32 s49, s46, 0x80
	s_addc_u32 s50, s5, 0
	s_add_u32 s51, s20, 0x100
	s_addc_u32 s54, s21, 0
	s_add_u32 s22, s10, 0x40080
	s_addc_u32 s23, s11, 0
	s_mov_b32 s55, -2
	s_mov_b64 s[20:21], 0
	v_lshl_add_u64 v[140:141], s[22:23], 0, v[136:137]
	v_lshl_add_u64 v[142:143], s[22:23], 0, v[138:139]
	s_add_u32 s22, s10, s20
	s_addc_u32 s23, s11, s21
	s_add_u32 s30, s22, 0x100
	s_addc_u32 s31, s23, 0
	s_add_u32 s56, s51, s20
	s_addc_u32 s57, s54, s21
	s_add_u32 s22, s22, 0x180
	s_addc_u32 s23, s23, 0
	s_add_i32 s58, 0, 0x10000
	v_add_u32_e32 v160, s58, v145
	ds_read_b128 v[148:151], v160
	ds_read_b128 v[152:155], v160 offset:1024
	ds_read_b128 v[156:159], v160 offset:2048
	ds_read_b128 v[160:163], v160 offset:3072
	s_cmpk_eq_i32 s20, 0x700
	s_cselect_b32 s29, s50, s23
	s_cselect_b32 s28, s49, s22
	s_cselect_b32 s23, s7, s57
	s_cselect_b32 s22, s47, s56
	s_cselect_b32 s31, s5, s31
	s_cselect_b32 s30, s46, s30
	v_lshl_add_u64 v[172:173], v[142:143], 0, s[20:21]
	s_add_i32 m0, s27, 0xc000
	ds_read_b128 v[164:167], v147
	ds_read_b128 v[168:171], v147 offset:1024
	ds_read_b128 v[192:195], v147 offset:2048
	ds_read_b128 v[196:199], v147 offset:3072
	ds_read_b128 v[200:203], v147 offset:4096
	ds_read_b128 v[204:207], v147 offset:5120
	ds_read_b128 v[208:211], v147 offset:6144
	ds_read_b128 v[212:215], v147 offset:7168
	global_load_lds_dwordx4 v[172:173], off
	v_lshl_add_u64 v[172:173], v[140:141], 0, s[20:21]
	s_add_i32 m0, s27, 0xe000
	s_nop 0
	global_load_lds_dwordx4 v[172:173], off
	s_waitcnt lgkmcnt(8)
	s_barrier
	s_waitcnt lgkmcnt(0)
	s_setprio 1
	s_waitcnt lgkmcnt(0)
	v_mfma_f32_16x16x32_bf16 v[126:129], v[148:151], v[164:167], 0
	v_mfma_f32_16x16x32_bf16 v[122:125], v[156:159], v[164:167], 0
	v_mfma_f32_16x16x32_bf16 v[118:121], v[148:151], v[192:195], 0
	v_mfma_f32_16x16x32_bf16 v[114:117], v[156:159], v[192:195], 0
	v_mfma_f32_16x16x32_bf16 v[102:105], v[148:151], v[200:203], 0
	v_mfma_f32_16x16x32_bf16 v[98:101], v[156:159], v[200:203], 0
	v_mfma_f32_16x16x32_bf16 v[86:89], v[148:151], v[208:211], 0
	v_mfma_f32_16x16x32_bf16 v[82:85], v[156:159], v[208:211], 0
	v_mfma_f32_16x16x32_bf16 v[126:129], v[152:155], v[168:171], v[126:129]
	v_mfma_f32_16x16x32_bf16 v[122:125], v[160:163], v[168:171], v[122:125]
	v_mfma_f32_16x16x32_bf16 v[118:121], v[152:155], v[196:199], v[118:121]
	v_mfma_f32_16x16x32_bf16 v[114:117], v[160:163], v[196:199], v[114:117]
	v_mfma_f32_16x16x32_bf16 v[102:105], v[152:155], v[204:207], v[102:105]
	v_mfma_f32_16x16x32_bf16 v[98:101], v[160:163], v[204:207], v[98:101]
	v_mfma_f32_16x16x32_bf16 v[86:89], v[152:155], v[212:215], v[86:89]
	v_mfma_f32_16x16x32_bf16 v[82:85], v[160:163], v[212:215], v[82:85]
	s_setprio 0
	s_barrier
	s_add_i32 s59, 0, 0x14000
	v_add_u32_e32 v172, s59, v145
	s_add_i32 s56, s58, s26
	ds_read_b128 v[216:219], v172
	ds_read_b128 v[220:223], v172 offset:1024
	ds_read_b128 v[224:227], v172 offset:2048
	ds_read_b128 v[228:231], v172 offset:3072
	v_lshl_add_u64 v[172:173], s[22:23], 0, v[0:1]
	s_mov_b32 m0, s56
	v_lshl_add_u64 v[232:233], s[22:23], 0, v[130:131]
	global_load_lds_dwordx4 v[172:173], off
	s_add_i32 m0, s56, 0x2000
	s_nop 0
	global_load_lds_dwordx4 v[232:233], off
	s_barrier
	s_waitcnt lgkmcnt(0)
	s_setprio 1
	s_waitcnt lgkmcnt(0)
	v_mfma_f32_16x16x32_bf16 v[110:113], v[216:219], v[164:167], 0
	v_mfma_f32_16x16x32_bf16 v[106:109], v[224:227], v[164:167], 0
	v_mfma_f32_16x16x32_bf16 v[94:97], v[216:219], v[192:195], 0
	v_mfma_f32_16x16x32_bf16 v[90:93], v[224:227], v[192:195], 0
	v_mfma_f32_16x16x32_bf16 v[78:81], v[216:219], v[200:203], 0
	v_mfma_f32_16x16x32_bf16 v[74:77], v[224:227], v[200:203], 0
	v_mfma_f32_16x16x32_bf16 v[70:73], v[216:219], v[208:211], 0
	v_mfma_f32_16x16x32_bf16 v[66:69], v[224:227], v[208:211], 0
	v_mfma_f32_16x16x32_bf16 v[110:113], v[220:223], v[168:171], v[110:113]
	v_mfma_f32_16x16x32_bf16 v[106:109], v[228:231], v[168:171], v[106:109]
	v_mfma_f32_16x16x32_bf16 v[94:97], v[220:223], v[196:199], v[94:97]
	v_mfma_f32_16x16x32_bf16 v[90:93], v[228:231], v[196:199], v[90:93]
	v_mfma_f32_16x16x32_bf16 v[78:81], v[220:223], v[204:207], v[78:81]
	v_mfma_f32_16x16x32_bf16 v[74:77], v[228:231], v[204:207], v[74:77]
	v_mfma_f32_16x16x32_bf16 v[70:73], v[220:223], v[212:215], v[70:73]
	v_mfma_f32_16x16x32_bf16 v[66:69], v[228:231], v[212:215], v[66:69]
	s_setprio 0
	s_mov_b32 m0, s27
	v_lshl_add_u64 v[234:235], s[30:31], 0, v[134:135]
	s_barrier
	ds_read_b128 v[164:167], v147 offset:16384
	ds_read_b128 v[168:171], v147 offset:17408
	ds_read_b128 v[192:195], v147 offset:18432
	ds_read_b128 v[196:199], v147 offset:19456
	ds_read_b128 v[200:203], v147 offset:20480
	ds_read_b128 v[204:207], v147 offset:21504
	ds_read_b128 v[208:211], v147 offset:22528
	ds_read_b128 v[212:215], v147 offset:23552
	global_load_lds_dwordx4 v[234:235], off
	v_lshl_add_u64 v[234:235], s[30:31], 0, v[132:133]
	s_mov_b32 m0, s34
	s_nop 0
	global_load_lds_dwordx4 v[234:235], off
	s_barrier
; #define PG8_STAGE(bufoff, gbase, voff) do { _Pragma("unroll") for (int _i = 0; _i < 2; ++_i) \
;         __builtin_amdgcn_global_load_lds((const unsigned*)((const char*)(gbase) + (voff)[_i]), (LAS unsigned*)(lds + (bufoff) + ldsw + _i * 8192), 16, 0, 0); } while (0)
; #define PG8_LDA(dst, b, h) do { _Pragma("unroll") for (int m = 0; m < 4; ++m) _Pragma("unroll") for (int k = 0; k < 2; ++k) dst[m][k] = *(const LAS bf16x8*)(lds + PG8_SA(b, h) + aoff + m * 2048 + k * 1024); } while (0)
; #define PG8_LDB(dst, b, h) do { _Pragma("unroll") for (int n = 0; n < 2; ++n) _Pragma("unroll") for (int k = 0; k < 2; ++k) dst[n][k] = *(const LAS bf16x8*)(lds + PG8_SB(b, h) + boff + n * 2048 + k * 1024); } while (0)
; #define PG8_MMA(ai, bj, At, Bt_) do { __builtin_amdgcn_s_setprio(1); _Pragma("unroll") for (int m = 0; m < 4; ++m) _Pragma("unroll") for (int n = 0; n < 2; ++n) _Pragma("unroll") for (int k = 0; k < 2; ++k) \
;         acc[ai][bj][m][n] = __builtin_amdgcn_mfma_f32_16x16x32_bf16(Bt_[n][k], At[m][k], acc[ai][bj][m][n], 0, 0, 0); __builtin_amdgcn_s_setprio(0); } while (0)
; #define PG8_WAIT_V(n) asm volatile("s_waitcnt vmcnt(" #n ")" ::: "memory")
; #define PG8_WAIT_L(n) asm volatile("s_waitcnt lgkmcnt(" #n ")" ::: "memory")
; #define PG8_BAR __builtin_amdgcn_s_barrier()
; #define PG8_SCHED __builtin_amdgcn_sched_barrier(0)
; template <bool REMAP>
; DI void gemm_phase(LAS unsigned char* lds, const u16* A, int lda, const u16* Bt, int K, u16* O, int ldc, int nunits) {
;     ...
;             PG8_BAR; PG8_WAIT_L(0); PG8_MMA(1, 0, At, B0); PG8_BAR; PG8_SCHED;
;             PG8_STAGE(PG8_SB(0, 1), b2 + hstepB, voffB);
;             PG8_WAIT_V(6); PG8_BAR; PG8_MMA(1, 1, At, B1); PG8_BAR;
;             PG8_LDB(B0, 1, 0); PG8_SCHED; PG8_LDA(At, 1, 0); PG8_STAGE(PG8_SA(0, 1), a2 + hstepA, voffA);
;             PG8_WAIT_L(8); PG8_BAR; PG8_WAIT_L(0); PG8_MMA(0, 0, At, B0); PG8_BAR; PG8_SCHED;
	s_waitcnt lgkmcnt(0)
	s_setprio 1
	s_waitcnt lgkmcnt(0)
	v_mfma_f32_16x16x32_bf16 v[62:65], v[148:151], v[164:167], 0
	v_mfma_f32_16x16x32_bf16 v[58:61], v[156:159], v[164:167], 0
	v_mfma_f32_16x16x32_bf16 v[54:57], v[148:151], v[192:195], 0
	v_mfma_f32_16x16x32_bf16 v[50:53], v[156:159], v[192:195], 0
	v_mfma_f32_16x16x32_bf16 v[38:41], v[148:151], v[200:203], 0
	v_mfma_f32_16x16x32_bf16 v[34:37], v[156:159], v[200:203], 0
	v_mfma_f32_16x16x32_bf16 v[22:25], v[148:151], v[208:211], 0
	v_mfma_f32_16x16x32_bf16 v[18:21], v[156:159], v[208:211], 0
	v_mfma_f32_16x16x32_bf16 v[62:65], v[152:155], v[168:171], v[62:65]
	v_mfma_f32_16x16x32_bf16 v[58:61], v[160:163], v[168:171], v[58:61]
	v_mfma_f32_16x16x32_bf16 v[54:57], v[152:155], v[196:199], v[54:57]
	v_mfma_f32_16x16x32_bf16 v[50:53], v[160:163], v[196:199], v[50:53]
	v_mfma_f32_16x16x32_bf16 v[38:41], v[152:155], v[204:207], v[38:41]
	v_mfma_f32_16x16x32_bf16 v[34:37], v[160:163], v[204:207], v[34:37]
	v_mfma_f32_16x16x32_bf16 v[22:25], v[152:155], v[212:215], v[22:25]
	v_mfma_f32_16x16x32_bf16 v[18:21], v[160:163], v[212:215], v[18:21]
	s_setprio 0
	s_barrier
	s_add_u32 s56, s22, 0x40000
	s_addc_u32 s57, s23, 0
	s_add_i32 s58, s59, s26
	v_lshl_add_u64 v[148:149], s[56:57], 0, v[0:1]
	s_mov_b32 m0, s58
	s_nop 0
	global_load_lds_dwordx4 v[148:149], off
	v_lshl_add_u64 v[148:149], s[56:57], 0, v[130:131]
	s_add_i32 m0, s58, 0x2000
	s_nop 0
	global_load_lds_dwordx4 v[148:149], off
	s_waitcnt vmcnt(6)
	s_barrier
	s_setprio 1
	v_mfma_f32_16x16x32_bf16 v[46:49], v[216:219], v[164:167], 0
	v_mfma_f32_16x16x32_bf16 v[42:45], v[224:227], v[164:167], 0
	v_mfma_f32_16x16x32_bf16 v[30:33], v[216:219], v[192:195], 0
	v_mfma_f32_16x16x32_bf16 v[26:29], v[224:227], v[192:195], 0
	v_mfma_f32_16x16x32_bf16 v[14:17], v[216:219], v[200:203], 0
	v_mfma_f32_16x16x32_bf16 v[10:13], v[224:227], v[200:203], 0
	v_mfma_f32_16x16x32_bf16 v[6:9], v[216:219], v[208:211], 0
	v_mfma_f32_16x16x32_bf16 v[2:5], v[224:227], v[208:211], 0
	v_mfma_f32_16x16x32_bf16 v[46:49], v[220:223], v[168:171], v[46:49]
	v_mfma_f32_16x16x32_bf16 v[42:45], v[228:231], v[168:171], v[42:45]
	v_mfma_f32_16x16x32_bf16 v[30:33], v[220:223], v[196:199], v[30:33]
	v_mfma_f32_16x16x32_bf16 v[26:29], v[228:231], v[196:199], v[26:29]
	v_mfma_f32_16x16x32_bf16 v[14:17], v[220:223], v[204:207], v[14:17]
	v_mfma_f32_16x16x32_bf16 v[10:13], v[228:231], v[204:207], v[10:13]
	v_mfma_f32_16x16x32_bf16 v[6:9], v[220:223], v[212:215], v[6:9]
	v_mfma_f32_16x16x32_bf16 v[2:5], v[228:231], v[212:215], v[2:5]
	s_setprio 0
	s_add_i32 s56, 0, 0x18000
	v_add_u32_e32 v160, s56, v145
	s_barrier
	ds_read_b128 v[148:151], v160
	ds_read_b128 v[152:155], v160 offset:1024
	ds_read_b128 v[156:159], v160 offset:2048
	ds_read_b128 v[160:163], v160 offset:3072
	s_add_u32 s30, s30, 0x40000
	s_addc_u32 s31, s31, 0
	s_mov_b32 m0, s35
	v_lshl_add_u64 v[216:217], s[30:31], 0, v[134:135]
	ds_read_b128 v[164:167], v147 offset:32768
	ds_read_b128 v[168:171], v147 offset:33792
	ds_read_b128 v[192:195], v147 offset:34816
	ds_read_b128 v[196:199], v147 offset:35840
	ds_read_b128 v[200:203], v147 offset:36864
	ds_read_b128 v[204:207], v147 offset:37888
	ds_read_b128 v[208:211], v147 offset:38912
	ds_read_b128 v[212:215], v147 offset:39936
	global_load_lds_dwordx4 v[216:217], off
	v_lshl_add_u64 v[216:217], s[30:31], 0, v[132:133]
	s_mov_b32 m0, s36
	s_nop 0
	global_load_lds_dwordx4 v[216:217], off
	s_waitcnt lgkmcnt(8)
	s_barrier
	s_waitcnt lgkmcnt(0)
	s_setprio 1
	s_waitcnt lgkmcnt(0)
	v_mfma_f32_16x16x32_bf16 v[126:129], v[148:151], v[164:167], v[126:129]
	v_mfma_f32_16x16x32_bf16 v[122:125], v[156:159], v[164:167], v[122:125]
	v_mfma_f32_16x16x32_bf16 v[118:121], v[148:151], v[192:195], v[118:121]
	v_mfma_f32_16x16x32_bf16 v[114:117], v[156:159], v[192:195], v[114:117]
	v_mfma_f32_16x16x32_bf16 v[102:105], v[148:151], v[200:203], v[102:105]
	v_mfma_f32_16x16x32_bf16 v[98:101], v[156:159], v[200:203], v[98:101]
	v_mfma_f32_16x16x32_bf16 v[86:89], v[148:151], v[208:211], v[86:89]
	v_mfma_f32_16x16x32_bf16 v[82:85], v[156:159], v[208:211], v[82:85]
	v_mfma_f32_16x16x32_bf16 v[126:129], v[152:155], v[168:171], v[126:129]
	v_mfma_f32_16x16x32_bf16 v[122:125], v[160:163], v[168:171], v[122:125]
	v_mfma_f32_16x16x32_bf16 v[118:121], v[152:155], v[196:199], v[118:121]
	v_mfma_f32_16x16x32_bf16 v[114:117], v[160:163], v[196:199], v[114:117]
	v_mfma_f32_16x16x32_bf16 v[102:105], v[152:155], v[204:207], v[102:105]
	v_mfma_f32_16x16x32_bf16 v[98:101], v[160:163], v[204:207], v[98:101]
	v_mfma_f32_16x16x32_bf16 v[86:89], v[152:155], v[212:215], v[86:89]
	v_mfma_f32_16x16x32_bf16 v[82:85], v[160:163], v[212:215], v[82:85]
	s_setprio 0
	s_barrier
; #define PG8_STAGE(bufoff, gbase, voff) do { _Pragma("unroll") for (int _i = 0; _i < 2; ++_i) \
;         __builtin_amdgcn_global_load_lds((const unsigned*)((const char*)(gbase) + (voff)[_i]), (LAS unsigned*)(lds + (bufoff) + ldsw + _i * 8192), 16, 0, 0); } while (0)
; #define PG8_LDA(dst, b, h) do { _Pragma("unroll") for (int m = 0; m < 4; ++m) _Pragma("unroll") for (int k = 0; k < 2; ++k) dst[m][k] = *(const LAS bf16x8*)(lds + PG8_SA(b, h) + aoff + m * 2048 + k * 1024); } while (0)
; #define PG8_LDB(dst, b, h) do { _Pragma("unroll") for (int n = 0; n < 2; ++n) _Pragma("unroll") for (int k = 0; k < 2; ++k) dst[n][k] = *(const LAS bf16x8*)(lds + PG8_SB(b, h) + boff + n * 2048 + k * 1024); } while (0)
; #define PG8_MMA(ai, bj, At, Bt_) do { __builtin_amdgcn_s_setprio(1); _Pragma("unroll") for (int m = 0; m < 4; ++m) _Pragma("unroll") for (int n = 0; n < 2; ++n) _Pragma("unroll") for (int k = 0; k < 2; ++k) \
;         acc[ai][bj][m][n] = __builtin_amdgcn_mfma_f32_16x16x32_bf16(Bt_[n][k], At[m][k], acc[ai][bj][m][n], 0, 0, 0); __builtin_amdgcn_s_setprio(0); } while (0)
; #define PG8_WAIT_V(n) asm volatile("s_waitcnt vmcnt(" #n ")" ::: "memory")
; #define PG8_WAIT_L(n) asm volatile("s_waitcnt lgkmcnt(" #n ")" ::: "memory")
; #define PG8_BAR __builtin_amdgcn_s_barrier()
; #define PG8_SCHED __builtin_amdgcn_sched_barrier(0)
; template <bool REMAP>
; DI void gemm_phase(LAS unsigned char* lds, const u16* A, int lda, const u16* Bt, int K, u16* O, int ldc, int nunits) {
;     ...
;             PG8_LDB(B1, 1, 1); PG8_STAGE(PG8_SB(1, 0), b3, voffB);
;             PG8_BAR; PG8_WAIT_L(0); PG8_MMA(0, 1, At, B1); PG8_BAR;
;             PG8_LDA(At, 1, 1); PG8_STAGE(PG8_SA(1, 0), a3, voffA);
;             PG8_BAR; PG8_WAIT_L(0); PG8_MMA(1, 0, At, B0); PG8_BAR; PG8_SCHED;
;             PG8_STAGE(PG8_SB(1, 1), b3 + hstepB, voffB);
;             PG8_WAIT_V(6); PG8_BAR; PG8_MMA(1, 1, At, B1); PG8_BAR;
;         }
	s_add_i32 s30, 0, 0x1c000
	s_add_i32 s31, s56, s26
	v_add_u32_e32 v228, s30, v145
	v_lshl_add_u64 v[172:173], v[172:173], 0, s[18:19]
	s_mov_b32 m0, s31
	ds_read_b128 v[216:219], v228
	ds_read_b128 v[220:223], v228 offset:1024
	ds_read_b128 v[224:227], v228 offset:2048
	ds_read_b128 v[228:231], v228 offset:3072
	global_load_lds_dwordx4 v[172:173], off
	v_lshl_add_u64 v[172:173], v[232:233], 0, s[18:19]
	s_add_i32 m0, s31, 0x2000
	s_nop 0
	global_load_lds_dwordx4 v[172:173], off
	s_barrier
	s_waitcnt lgkmcnt(0)
	s_setprio 1
	s_waitcnt lgkmcnt(0)
	v_mfma_f32_16x16x32_bf16 v[110:113], v[216:219], v[164:167], v[110:113]
	v_mfma_f32_16x16x32_bf16 v[106:109], v[224:227], v[164:167], v[106:109]
	v_mfma_f32_16x16x32_bf16 v[94:97], v[216:219], v[192:195], v[94:97]
	v_mfma_f32_16x16x32_bf16 v[90:93], v[224:227], v[192:195], v[90:93]
	v_mfma_f32_16x16x32_bf16 v[78:81], v[216:219], v[200:203], v[78:81]
	v_mfma_f32_16x16x32_bf16 v[74:77], v[224:227], v[200:203], v[74:77]
	v_mfma_f32_16x16x32_bf16 v[70:73], v[216:219], v[208:211], v[70:73]
	v_mfma_f32_16x16x32_bf16 v[66:69], v[224:227], v[208:211], v[66:69]
	v_mfma_f32_16x16x32_bf16 v[110:113], v[220:223], v[168:171], v[110:113]
	v_mfma_f32_16x16x32_bf16 v[106:109], v[228:231], v[168:171], v[106:109]
	v_mfma_f32_16x16x32_bf16 v[94:97], v[220:223], v[196:199], v[94:97]
	v_mfma_f32_16x16x32_bf16 v[90:93], v[228:231], v[196:199], v[90:93]
	v_mfma_f32_16x16x32_bf16 v[78:81], v[220:223], v[204:207], v[78:81]
	v_mfma_f32_16x16x32_bf16 v[74:77], v[228:231], v[204:207], v[74:77]
	v_mfma_f32_16x16x32_bf16 v[70:73], v[220:223], v[212:215], v[70:73]
	v_mfma_f32_16x16x32_bf16 v[66:69], v[228:231], v[212:215], v[66:69]
	s_setprio 0
	s_mov_b32 m0, s37
	v_lshl_add_u64 v[172:173], s[28:29], 0, v[134:135]
	s_barrier
	ds_read_b128 v[164:167], v147 offset:49152
	ds_read_b128 v[168:171], v147 offset:50176
	ds_read_b128 v[192:195], v147 offset:51200
	ds_read_b128 v[196:199], v147 offset:52224
	ds_read_b128 v[200:203], v147 offset:53248
	ds_read_b128 v[204:207], v147 offset:54272
	ds_read_b128 v[208:211], v147 offset:55296
	ds_read_b128 v[212:215], v147 offset:56320
	global_load_lds_dwordx4 v[172:173], off
	v_lshl_add_u64 v[172:173], s[28:29], 0, v[132:133]
	s_mov_b32 m0, s38
	s_nop 0
	global_load_lds_dwordx4 v[172:173], off
	s_barrier
	s_waitcnt lgkmcnt(0)
	s_setprio 1
	s_waitcnt lgkmcnt(0)
	v_mfma_f32_16x16x32_bf16 v[62:65], v[148:151], v[164:167], v[62:65]
	v_mfma_f32_16x16x32_bf16 v[58:61], v[156:159], v[164:167], v[58:61]
	v_mfma_f32_16x16x32_bf16 v[54:57], v[148:151], v[192:195], v[54:57]
	v_mfma_f32_16x16x32_bf16 v[50:53], v[156:159], v[192:195], v[50:53]
	v_mfma_f32_16x16x32_bf16 v[38:41], v[148:151], v[200:203], v[38:41]
	v_mfma_f32_16x16x32_bf16 v[34:37], v[156:159], v[200:203], v[34:37]
	v_mfma_f32_16x16x32_bf16 v[22:25], v[148:151], v[208:211], v[22:25]
	v_mfma_f32_16x16x32_bf16 v[18:21], v[156:159], v[208:211], v[18:21]
	v_mfma_f32_16x16x32_bf16 v[62:65], v[152:155], v[168:171], v[62:65]
	v_mfma_f32_16x16x32_bf16 v[58:61], v[160:163], v[168:171], v[58:61]
	v_mfma_f32_16x16x32_bf16 v[54:57], v[152:155], v[196:199], v[54:57]
	v_mfma_f32_16x16x32_bf16 v[50:53], v[160:163], v[196:199], v[50:53]
	v_mfma_f32_16x16x32_bf16 v[38:41], v[152:155], v[204:207], v[38:41]
	v_mfma_f32_16x16x32_bf16 v[34:37], v[160:163], v[204:207], v[34:37]
	v_mfma_f32_16x16x32_bf16 v[22:25], v[152:155], v[212:215], v[22:25]
	v_mfma_f32_16x16x32_bf16 v[18:21], v[160:163], v[212:215], v[18:21]
	s_setprio 0
	s_barrier
	s_add_u32 s22, s22, 0x40080
	s_addc_u32 s23, s23, 0
	s_add_i32 s28, s30, s26
	v_lshl_add_u64 v[148:149], s[22:23], 0, v[0:1]
	s_mov_b32 m0, s28
	s_nop 0
	global_load_lds_dwordx4 v[148:149], off
	v_lshl_add_u64 v[148:149], s[22:23], 0, v[130:131]
	s_add_i32 m0, s28, 0x2000
	s_nop 0
	global_load_lds_dwordx4 v[148:149], off
	s_waitcnt vmcnt(6)
	s_barrier
	s_setprio 1
	v_mfma_f32_16x16x32_bf16 v[46:49], v[216:219], v[164:167], v[46:49]
	v_mfma_f32_16x16x32_bf16 v[42:45], v[224:227], v[164:167], v[42:45]
	v_mfma_f32_16x16x32_bf16 v[30:33], v[216:219], v[192:195], v[30:33]
	v_mfma_f32_16x16x32_bf16 v[26:29], v[224:227], v[192:195], v[26:29]
	v_mfma_f32_16x16x32_bf16 v[14:17], v[216:219], v[200:203], v[14:17]
	v_mfma_f32_16x16x32_bf16 v[10:13], v[224:227], v[200:203], v[10:13]
	v_mfma_f32_16x16x32_bf16 v[6:9], v[216:219], v[208:211], v[6:9]
	v_mfma_f32_16x16x32_bf16 v[2:5], v[224:227], v[208:211], v[2:5]
	v_mfma_f32_16x16x32_bf16 v[46:49], v[220:223], v[168:171], v[46:49]
	v_mfma_f32_16x16x32_bf16 v[42:45], v[228:231], v[168:171], v[42:45]
	v_mfma_f32_16x16x32_bf16 v[30:33], v[220:223], v[196:199], v[30:33]
	v_mfma_f32_16x16x32_bf16 v[26:29], v[228:231], v[196:199], v[26:29]
	v_mfma_f32_16x16x32_bf16 v[14:17], v[220:223], v[204:207], v[14:17]
	v_mfma_f32_16x16x32_bf16 v[10:13], v[228:231], v[204:207], v[10:13]
	v_mfma_f32_16x16x32_bf16 v[6:9], v[220:223], v[212:215], v[6:9]
	v_mfma_f32_16x16x32_bf16 v[2:5], v[228:231], v[212:215], v[2:5]
	s_setprio 0
	s_add_i32 s55, s55, 2
	s_add_u32 s20, s20, 0x100
	s_addc_u32 s21, s21, 0
	s_cmp_gt_u32 s55, 13
	s_barrier
